# attn0 work items dealt XCD-major so a (batch, head)'s K/V stay in one L2
# baseline (speedup 1.0000x reference)
_Z4mega6Params:
	s_mov_b64 s[38:39], s[0:1]
	s_mov_b32 s1, 0
	s_mov_b32 s87, s2
	s_and_b32 s100, s2, 7
	s_lshl_b32 s100, s100, 5
	s_lshr_b32 s101, s2, 3
	s_or_b32 s100, s100, s101
	v_writelane_b32 v254, s0, 0
	s_getreg_b32 s2, hwreg(HW_REG_XCC_ID, 0, 4)
	v_cmp_eq_u32_e64 s[56:57], 0, v0
	v_writelane_b32 v254, s1, 1
	s_and_saveexec_b64 s[0:1], s[56:57]
	s_cbranch_execz .LBB0_3
	s_add_i32 s3, 0, 0x20000
	v_mov_b32_e32 v1, 0
	v_mov_b32_e32 v2, s3
	s_add_i32 s3, 0, 0x20004
	s_mov_b64 s[4:5], exec
	ds_write_b32 v2, v1
	v_mov_b32_e32 v2, s3
	ds_write_b32 v2, v1
	v_mbcnt_lo_u32_b32 v1, s4, 0
	v_mbcnt_hi_u32_b32 v1, s5, v1
	v_cmp_eq_u32_e32 vcc, 0, v1
	s_and_b64 s[6:7], exec, vcc
	s_mov_b64 exec, s[6:7]
	s_cbranch_execz .LBB0_3
	s_load_dwordx2 s[6:7], s[38:39], 0x178
	s_lshl_b32 s2, s2, 8
	s_and_b32 s2, s2, 0xf00
	v_mov_b32_e32 v1, 0x13ca0000
	s_waitcnt lgkmcnt(0)
	s_add_u32 s2, s6, s2
	s_addc_u32 s3, s7, 0
	s_bcnt1_i32_b64 s4, s[4:5]
	v_mov_b32_e32 v2, s4
	global_atomic_add v1, v2, s[2:3] offset:1024

.LBB0_585:
	s_andn2_b64 vcc, exec, s[0:1]
	s_cbranch_vccnz .LBB0_692
	v_mov_b32_e32 v2, v0
	v_mov_b32_e32 v4, v0
	s_mov_b32 s0, s100
	v_mov_b32_e32 v1, v0
	s_nop 0
	v_ashrrev_i32_e32 v1, 8, v1
	v_lshl_add_u32 v1, s0, 1, v1
	s_movk_i32 s0, 0x400
	v_cmp_gt_i32_e32 vcc, s0, v1
	s_and_saveexec_b64 s[6:7], vcc
	v_readlane_b32 s18, v254, 24
	v_readlane_b32 s40, v254, 18
	v_readlane_b32 s19, v254, 25
	v_readlane_b32 s41, v254, 19
	s_cbranch_execz .LBB0_691
	v_lshrrev_b32_e32 v9, 1, v4
	v_and_b32_e32 v154, 31, v4
	v_and_b32_e32 v163, 32, v9
	s_load_dword s0, s[20:21], 0x0
	v_lshlrev_b32_e32 v2, 8, v2
	v_bfe_u32 v8, v4, 5, 1
	v_or_b32_e32 v165, v163, v154
	v_and_b32_e32 v5, 0xffff0000, v2
	v_and_b32_e32 v150, 0xff, v4
	v_lshlrev_b32_e32 v2, 7, v154
	v_lshlrev_b32_e32 v156, 3, v8
	v_bfe_u32 v157, v4, 7, 1
	v_sub_u32_e64 v4, v165, 8 clamp
	v_lshl_add_u64 v[6:7], s[36:37], 0, v[2:3]
	v_lshlrev_b32_e32 v2, 4, v8
	v_min_u32_e32 v167, 48, v4
	v_lshl_or_b32 v4, v154, 8, v156
	v_add_u32_e32 v151, 0, v5
	v_lshl_add_u64 v[152:153], v[6:7], 0, v[2:3]
	v_lshl_or_b32 v162, v154, 6, v156
	v_lshl_or_b32 v2, v154, 13, v156
	v_lshlrev_b32_e32 v6, 10, v154
	v_lshlrev_b32_e32 v174, 2, v8
	v_or_b32_e32 v8, 0x2000, v4
	v_lshl_or_b32 v5, v150, 2, v5
	v_and_b32_e32 v155, 0x60, v9
	v_or_b32_e32 v164, 16, v162
	v_or_b32_e32 v166, 32, v162
	v_or_b32_e32 v168, 48, v162
	v_or_b32_e32 v170, 0x40000, v2
	v_or_b32_e32 v172, 0x40010, v2
	v_add_u32_e32 v169, 16, v167
	s_waitcnt lgkmcnt(0)
	s_lshl_b32 s2, s0, 1
	v_or_b32_e32 v171, 1, v174
	v_or_b32_e32 v173, 2, v174
	v_or_b32_e32 v175, 3, v174
	v_or_b32_e32 v204, 8, v174
	v_or_b32_e32 v205, 9, v174
	v_or_b32_e32 v206, 10, v174
	v_or_b32_e32 v207, 11, v174
	v_or_b32_e32 v208, 17, v174
	v_or_b32_e32 v209, 18, v174
	v_or_b32_e32 v210, 19, v174
	v_or_b32_e32 v211, 24, v174
	v_or_b32_e32 v212, 25, v174
	v_or_b32_e32 v213, 26, v174
	v_or_b32_e32 v214, 27, v174
	v_or_b32_e32 v215, 0xffffff00, v150
	v_add_u32_e32 v216, 0, v5
	s_mov_b64 s[8:9], 0
	v_lshlrev_b32_e32 v176, 1, v2
	v_lshlrev_b32_e32 v178, 1, v4
	v_lshlrev_b32_e32 v180, 1, v8
	v_lshlrev_b32_e32 v182, 1, v6
	v_lshlrev_b32_e32 v184, 1, v174
	s_branch .LBB0_590

	.amdhsa_kernel _Z4mega6Params
		.amdhsa_group_segment_fixed_size 0
		.amdhsa_private_segment_fixed_size 0
		.amdhsa_kernarg_size 640
		.amdhsa_user_sgpr_count 2
		.amdhsa_user_sgpr_dispatch_ptr 0
		.amdhsa_user_sgpr_queue_ptr 0
		.amdhsa_user_sgpr_kernarg_segment_ptr 1
		.amdhsa_user_sgpr_dispatch_id 0
		.amdhsa_user_sgpr_kernarg_preload_length 0
		.amdhsa_user_sgpr_kernarg_preload_offset 0
		.amdhsa_user_sgpr_private_segment_size 0
		.amdhsa_uses_dynamic_stack 0
		.amdhsa_enable_private_segment 0
		.amdhsa_system_sgpr_workgroup_id_x 1
		.amdhsa_system_sgpr_workgroup_id_y 0
		.amdhsa_system_sgpr_workgroup_id_z 0
		.amdhsa_system_sgpr_workgroup_info 0
		.amdhsa_system_vgpr_workitem_id 0
		.amdhsa_next_free_vgpr 256
		.amdhsa_next_free_sgpr 102
		.amdhsa_accum_offset 256
		.amdhsa_reserve_vcc 1
		.amdhsa_float_round_mode_32 0
		.amdhsa_float_round_mode_16_64 0
		.amdhsa_float_denorm_mode_32 3
		.amdhsa_float_denorm_mode_16_64 3
		.amdhsa_dx10_clamp 1
		.amdhsa_ieee_mode 1
		.amdhsa_fp16_overflow 0
		.amdhsa_tg_split 0
		.amdhsa_exception_fp_ieee_invalid_op 0
		.amdhsa_exception_fp_denorm_src 0
		.amdhsa_exception_fp_ieee_div_zero 0
		.amdhsa_exception_fp_ieee_overflow 0
		.amdhsa_exception_fp_ieee_underflow 0
		.amdhsa_exception_fp_ieee_inexact 0
		.amdhsa_exception_int_div_zero 0
	.end_amdhsa_kernel

amdhsa.kernels:
  - .agpr_count:     0
    .args:
      - .offset:         0
        .size:           384
        .value_kind:     by_value
      - .offset:         384
        .size:           4
        .value_kind:     hidden_block_count_x
      - .offset:         388
        .size:           4
        .value_kind:     hidden_block_count_y
      - .offset:         392
        .size:           4
        .value_kind:     hidden_block_count_z
      - .offset:         396
        .size:           2
        .value_kind:     hidden_group_size_x
      - .offset:         398
        .size:           2
        .value_kind:     hidden_group_size_y
      - .offset:         400
        .size:           2
        .value_kind:     hidden_group_size_z
      - .offset:         402
        .size:           2
        .value_kind:     hidden_remainder_x
      - .offset:         404
        .size:           2
        .value_kind:     hidden_remainder_y
      - .offset:         406
        .size:           2
        .value_kind:     hidden_remainder_z
      - .offset:         424
        .size:           8
        .value_kind:     hidden_global_offset_x
      - .offset:         432
        .size:           8
        .value_kind:     hidden_global_offset_y
      - .offset:         440
        .size:           8
        .value_kind:     hidden_global_offset_z
      - .offset:         448
        .size:           2
        .value_kind:     hidden_grid_dims
      - .offset:         504
        .size:           4
        .value_kind:     hidden_dynamic_lds_size
    .group_segment_fixed_size: 0
    .kernarg_segment_align: 8
    .kernarg_segment_size: 640
    .language:       OpenCL C
    .language_version:
      - 2
      - 0
    .max_flat_workgroup_size: 512
    .name:           _Z4mega6Params
    .private_segment_fixed_size: 0
    .sgpr_count:     108
    .sgpr_spill_count: 106
    .symbol:         _Z4mega6Params.kd
    .uniform_work_group_size: 1
    .uses_dynamic_stack: false
    .vgpr_count:     256
    .vgpr_spill_count: 0
    .wavefront_size: 64
